# HGRN scan: units split over 2 WGs by value-column halves (all 256 CUs), MFMA part on waves 0-3 only, waves 4-7 staging-only loop; plus L1 attn Q-prep loads batched
# speedup vs baseline: 1.0197x; 1.0197x over previous
; DI float bflo(unsigned w) { return __uint_as_float(w << 16); }
; DI float bfhi(unsigned w) { return __uint_as_float(w & 0xffff0000u); }
; template <int DQK, int MODE>
; DI void attn_phase(const bf16_t* __restrict__ QK, int ldq, const bf16_t* __restrict__ Vt, int VC, bf16_t* __restrict__ O, int ldo, int nhu, bool skip_ctx, const float* __restrict__ qgain, const f32x2* __restrict__ rope, float qscale, char* shm) {
;     ...
;         for (int ks = 0; ks < DQK / 16; ++ks) qf[ks] = *(const bf16x8*)(QK + qrow * ldq + qoff + ks * 16 + h * 8);
;         {
;             float ss = 0.f;
; #pragma unroll
;             for (int ks = 0; ks < DQK / 16; ++ks) { const u32x4 wq = __builtin_bit_cast(u32x4, qf[ks]);
;                 const float a0 = bflo(wq.x), a1 = bfhi(wq.x), a2 = bflo(wq.y), a3 = bfhi(wq.y), a4 = bflo(wq.z), a5 = bfhi(wq.z), a6 = bflo(wq.w), a7 = bfhi(wq.w);
;                 ss += a0 * a0 + a1 * a1 + a2 * a2 + a3 * a3 + a4 * a4 + a5 * a5 + a6 * a6 + a7 * a7; }
;             ss += __shfl_xor(ss, 32);
;             const float rr = rsqrtf(ss * (1.f / DQK) + EPS) * qscale; int go = (MODE == 0 ? (hu & 1) * 64 : 0) + h * 8; asm volatile("" : "+v"(go));
;             const float* gq = qgain + go; const f32x2* rp = rope + (size_t)((qt > 0 ? qt - 1 : 0) * 256 + w * 32 + r) * (DQK / 2) + h * 8;
; #pragma unroll
;             for (int ks = 0; ks < DQK / 32; ++ks) {
;                 const u32x4 wa = __builtin_bit_cast(u32x4, qf[ks]), wb = __builtin_bit_cast(u32x4, qf[ks + DQK / 32]);
;                 float xa[8] = {bflo(wa.x), bfhi(wa.x), bflo(wa.y), bfhi(wa.y), bflo(wa.z), bfhi(wa.z), bflo(wa.w), bfhi(wa.w)};
;                 float xb[8] = {bflo(wb.x), bfhi(wb.x), bflo(wb.y), bfhi(wb.y), bflo(wb.z), bfhi(wb.z), bflo(wb.w), bfhi(wb.w)};
; #pragma unroll
;                 for (int j = 0; j < 8; ++j) { float x1 = xa[j] * rr * gq[ks * 16 + j], x2 = xb[j] * rr * gq[(ks + DQK / 32) * 16 + j];
;                     if (qt > 0) { const f32x2 cs = rp[ks * 16 + j]; const float y1 = x1 * cs[0] - x2 * cs[1], y2 = x1 * cs[1] + x2 * cs[0]; x1 = y1; x2 = y2; }
.LBB0_1292:
	s_lshl_b32 s12, s31, 6
	s_cmp_lg_u32 s0, 0
	s_cselect_b64 s[14:15], -1, 0
	s_mul_i32 s11, s10, 0x900
	s_lshl_b32 s13, s0, 8
	s_mul_hi_i32 s1, s10, 0x900
	s_add_u32 s34, s13, s11
	s_addc_u32 s35, 0, s1
	v_lshl_add_u64 v[0:1], s[34:35], 0, v[124:125]
	v_lshlrev_b64 v[148:149], 12, v[0:1]
	s_ashr_i32 s13, s12, 31
	v_lshl_add_u64 v[0:1], s[96:97], 0, v[148:149]
	v_lshl_add_u64 v[0:1], s[12:13], 1, v[0:1]
	v_lshl_add_u64 v[0:1], v[0:1], 0, v[128:129]
	global_load_dwordx4 v[2:5], v[0:1], off offset:64
	global_load_dwordx4 v[18:21], v[0:1], off
	global_load_dwordx4 v[12:15], v[0:1], off offset:96
	global_load_dwordx4 v[38:41], v[0:1], off offset:32
	v_and_or_b32 v0, s12, 64, v126
	v_readlane_b32 s36, v254, 7
	v_readlane_b32 s44, v254, 15
	v_ashrrev_i32_e32 v1, 31, v0
	v_readlane_b32 s45, v254, 16
	s_max_u32 s1, s0, 1
	s_cmp_eq_u32 s0, 0
	v_lshl_add_u64 v[0:1], v[0:1], 2, s[44:45]
	global_load_dword v200, v[0:1], off
	global_load_dword v201, v[0:1], off offset:128
	global_load_dword v202, v[0:1], off offset:4
	global_load_dword v203, v[0:1], off offset:132
	global_load_dword v204, v[0:1], off offset:8
	global_load_dword v205, v[0:1], off offset:136
	global_load_dword v206, v[0:1], off offset:12
	global_load_dword v207, v[0:1], off offset:140
	global_load_dword v208, v[0:1], off offset:16
	global_load_dword v209, v[0:1], off offset:144
	global_load_dword v210, v[0:1], off offset:20
	global_load_dword v211, v[0:1], off offset:148
	global_load_dword v212, v[0:1], off offset:24
	global_load_dword v213, v[0:1], off offset:152
	global_load_dword v214, v[0:1], off offset:28
	global_load_dword v215, v[0:1], off offset:156
	global_load_dword v216, v[0:1], off offset:64
	global_load_dword v217, v[0:1], off offset:192
	global_load_dword v218, v[0:1], off offset:68
	global_load_dword v219, v[0:1], off offset:196
	global_load_dword v220, v[0:1], off offset:72
	global_load_dword v221, v[0:1], off offset:200
	global_load_dword v222, v[0:1], off offset:76
	global_load_dword v223, v[0:1], off offset:204
	global_load_dword v224, v[0:1], off offset:80
	global_load_dword v225, v[0:1], off offset:208
	global_load_dword v226, v[0:1], off offset:84
	global_load_dword v227, v[0:1], off offset:212
	global_load_dword v228, v[0:1], off offset:88
	global_load_dword v229, v[0:1], off offset:216
	global_load_dword v246, v[0:1], off offset:92
	global_load_dword v247, v[0:1], off offset:220
	v_lshl_add_u32 v166, s1, 8, v157
	v_ashrrev_i32_e32 v167, 31, v166
	v_lshlrev_b64 v[166:167], 8, v[166:167]
	v_lshl_add_u64 v[166:167], v[130:131], 0, v[166:167]
	global_load_dwordx4 v[168:171], v[166:167], off
	global_load_dwordx4 v[172:175], v[166:167], off offset:16
	global_load_dwordx4 v[176:179], v[166:167], off offset:32
	global_load_dwordx4 v[180:183], v[166:167], off offset:48
	global_load_dwordx4 v[184:187], v[166:167], off offset:128
	global_load_dwordx4 v[188:191], v[166:167], off offset:144
	global_load_dwordx4 v[192:195], v[166:167], off offset:160
	global_load_dwordx4 v[196:199], v[166:167], off offset:176
	v_readlane_b32 s37, v254, 8
	v_readlane_b32 s38, v254, 9
	v_readlane_b32 s39, v254, 10
	v_readlane_b32 s40, v254, 11
	v_readlane_b32 s41, v254, 12
	v_readlane_b32 s42, v254, 13
	v_readlane_b32 s43, v254, 14
	v_readlane_b32 s46, v254, 17
	v_readlane_b32 s47, v254, 18
	v_readlane_b32 s48, v254, 19
	v_readlane_b32 s49, v254, 20
	v_readlane_b32 s50, v254, 21
	v_readlane_b32 s51, v254, 22
	s_waitcnt vmcnt(43)
	v_and_b32_e32 v7, 0xffff0000, v2
	s_waitcnt vmcnt(42)
	v_and_b32_e32 v6, 0xffff0000, v18
	v_lshlrev_b32_e32 v11, 16, v3
	s_waitcnt vmcnt(40)
	v_and_b32_e32 v32, 0xffff0000, v38
	v_and_b32_e32 v17, 0xffff0000, v3
	v_lshlrev_b32_e32 v31, 16, v5
	v_lshlrev_b32_e32 v30, 16, v21
	v_and_b32_e32 v35, 0xffff0000, v5
	v_and_b32_e32 v34, 0xffff0000, v21
	v_lshlrev_b32_e32 v36, 16, v38
	v_and_b32_e32 v33, 0xffff0000, v12
	v_lshlrev_b32_e32 v29, 16, v13
	v_and_b32_e32 v25, 0xffff0000, v13
	v_lshlrev_b32_e32 v21, 16, v14
	v_and_b32_e32 v13, 0xffff0000, v14
	v_lshlrev_b32_e32 v9, 16, v15
	v_and_b32_e32 v5, 0xffff0000, v15
	v_lshlrev_b32_e32 v3, 16, v2
	v_lshlrev_b32_e32 v2, 16, v18
	v_mov_b32_e32 v14, v6
	v_mov_b32_e32 v15, v32
	v_lshlrev_b32_e32 v10, 16, v19
	v_lshlrev_b32_e32 v37, 16, v12
	v_lshlrev_b32_e32 v28, 16, v39
	v_mov_b32_e32 v50, v2
	v_mov_b32_e32 v51, v36
	v_mov_b32_e32 v52, v7
	v_mov_b32_e32 v53, v33
	v_pk_mul_f32 v[14:15], v[14:15], v[14:15]
	v_and_b32_e32 v16, 0xffff0000, v19
	v_and_b32_e32 v24, 0xffff0000, v39
	v_mov_b32_e32 v18, v10
	v_mov_b32_e32 v19, v28
	v_mov_b32_e32 v66, v3
	v_mov_b32_e32 v67, v37
	v_pk_mul_f32 v[52:53], v[52:53], v[52:53]
	v_pk_fma_f32 v[14:15], v[50:51], v[50:51], v[14:15]
	v_lshlrev_b32_e32 v22, 16, v20
	v_and_b32_e32 v26, 0xffff0000, v20
	v_lshlrev_b32_e32 v20, 16, v40
	v_mov_b32_e32 v38, v16
	v_mov_b32_e32 v39, v24
	v_mov_b32_e32 v54, v11
	v_mov_b32_e32 v55, v29
	v_pk_fma_f32 v[50:51], v[66:67], v[66:67], v[52:53]
	v_pk_fma_f32 v[14:15], v[18:19], v[18:19], v[14:15]
	v_lshlrev_b32_e32 v23, 16, v4
	v_and_b32_e32 v27, 0xffff0000, v4
	v_and_b32_e32 v12, 0xffff0000, v40
	v_lshlrev_b32_e32 v8, 16, v41
	v_and_b32_e32 v4, 0xffff0000, v41
	v_mov_b32_e32 v40, v22
	v_mov_b32_e32 v41, v20
	v_mov_b32_e32 v56, v17
	v_mov_b32_e32 v57, v25
	v_pk_fma_f32 v[18:19], v[54:55], v[54:55], v[50:51]
	v_pk_fma_f32 v[14:15], v[38:39], v[38:39], v[14:15]
	v_mov_b32_e32 v44, v26
	v_mov_b32_e32 v45, v12
	v_mov_b32_e32 v58, v23
	v_mov_b32_e32 v59, v21
	v_pk_fma_f32 v[18:19], v[56:57], v[56:57], v[18:19]
	v_pk_fma_f32 v[14:15], v[40:41], v[40:41], v[14:15]
	v_mov_b32_e32 v46, v30
	v_mov_b32_e32 v47, v8
	v_mov_b32_e32 v60, v27
	v_mov_b32_e32 v61, v13
	v_pk_fma_f32 v[14:15], v[44:45], v[44:45], v[14:15]
	v_pk_fma_f32 v[18:19], v[58:59], v[58:59], v[18:19]
	v_mov_b32_e32 v48, v34
	v_mov_b32_e32 v49, v4
	v_mov_b32_e32 v62, v31
	v_mov_b32_e32 v63, v9
	v_pk_fma_f32 v[14:15], v[46:47], v[46:47], v[14:15]
	v_pk_fma_f32 v[18:19], v[60:61], v[60:61], v[18:19]
	v_mov_b32_e32 v64, v35
	v_mov_b32_e32 v65, v5
	v_pk_fma_f32 v[14:15], v[48:49], v[48:49], v[14:15]
	v_pk_fma_f32 v[18:19], v[62:63], v[62:63], v[18:19]
	v_add_f32_e32 v14, v14, v15
	v_pk_fma_f32 v[18:19], v[64:65], v[64:65], v[18:19]
	s_nop 0
	v_add_f32_e32 v14, v14, v18
	v_add_f32_e32 v15, v14, v19
	ds_bpermute_b32 v18, v127, v15
	v_lshl_add_u32 v14, s1, 8, v157
	s_waitcnt lgkmcnt(0)
	v_add_f32_e32 v15, v15, v18
	v_fmamk_f32 v15, v15, 0x3c800000, v164
	v_mul_f32_e32 v18, 0x4b800000, v15
	v_cmp_gt_f32_e32 vcc, s30, v15
	s_nop 1
	v_cndmask_b32_e32 v15, v15, v18, vcc
	v_rsq_f32_e32 v18, v15
	v_ashrrev_i32_e32 v15, 31, v14
	v_lshlrev_b64 v[14:15], 8, v[14:15]
	v_lshl_add_u64 v[14:15], v[130:131], 0, v[14:15]
	v_mul_f32_e32 v19, 0x45800000, v18
	v_cndmask_b32_e32 v18, v18, v19, vcc
	v_mul_f32_e32 v18, 0x3e38aa3b, v18
	v_pk_mul_f32 v[2:3], v[18:19], v[2:3] op_sel_hi:[0,1]
	s_waitcnt vmcnt(0)
	v_pk_mul_f32 v[2:3], v[200:201], v[2:3]
	s_cbranch_scc1 .LBB0_1294
; DI unsigned pack2(float lo, float hi) { const f32x2 v = (f32x2){lo, hi}; return __builtin_bit_cast(unsigned, __builtin_convertvector(v, bf16x2_t)); }
; DI float bflo(unsigned w) { return __uint_as_float(w << 16); }
; DI float bfhi(unsigned w) { return __uint_as_float(w & 0xffff0000u); }
; template <int DQK, int MODE>
; DI void attn_phase(const bf16_t* __restrict__ QK, int ldq, const bf16_t* __restrict__ Vt, int VC, bf16_t* __restrict__ O, int ldo, int nhu, bool skip_ctx, const float* __restrict__ qgain, const f32x2* __restrict__ rope, float qscale, char* shm) {
;     ...
;             for (int ks = 0; ks < DQK / 32; ++ks) {
;                 const u32x4 wa = __builtin_bit_cast(u32x4, qf[ks]), wb = __builtin_bit_cast(u32x4, qf[ks + DQK / 32]);
;                 float xa[8] = {bflo(wa.x), bfhi(wa.x), bflo(wa.y), bfhi(wa.y), bflo(wa.z), bfhi(wa.z), bflo(wa.w), bfhi(wa.w)};
;                 float xb[8] = {bflo(wb.x), bfhi(wb.x), bflo(wb.y), bfhi(wb.y), bflo(wb.z), bfhi(wb.z), bflo(wb.w), bfhi(wb.w)};
; #pragma unroll
;                 for (int j = 0; j < 8; ++j) { float x1 = xa[j] * rr * gq[ks * 16 + j], x2 = xb[j] * rr * gq[(ks + DQK / 32) * 16 + j];
;                     if (qt > 0) { const f32x2 cs = rp[ks * 16 + j]; const float y1 = x1 * cs[0] - x2 * cs[1], y2 = x1 * cs[1] + x2 * cs[0]; x1 = y1; x2 = y2; }
;                     xa[j] = x1; xb[j] = x2; }
;                 qf[ks] = __builtin_bit_cast(bf16x8, (u32x4){pack2(xa[0], xa[1]), pack2(xa[2], xa[3]), pack2(xa[4], xa[5]), pack2(xa[6], xa[7])});
;                 qf[ks + DQK / 32] = __builtin_bit_cast(bf16x8, (u32x4){pack2(xb[0], xb[1]), pack2(xb[2], xb[3]), pack2(xb[4], xb[5]), pack2(xb[6], xb[7])});
;             }
	v_pk_mul_f32 v[42:43], v[2:3], v[168:169] op_sel:[1,1] op_sel_hi:[1,0]
	v_pk_mul_f32 v[40:41], v[2:3], v[168:169]
	v_pk_fma_f32 v[2:3], v[2:3], v[168:169], v[42:43] op_sel_hi:[0,1,1]
	v_sub_f32_e32 v2, v40, v42
.LBB0_1294:
	v_mov_b32_e32 v19, v18
	v_pk_mul_f32 v[6:7], v[18:19], v[6:7]
	v_cndmask_b32_e64 v40, 0, 1, s[14:15]
	v_cmp_ne_u32_e64 s[0:1], 1, v40
	s_andn2_b64 vcc, exec, s[14:15]
	v_pk_mul_f32 v[6:7], v[6:7], v[202:203]
	s_cbranch_vccnz .LBB0_1296
	v_pk_mul_f32 v[42:43], v[6:7], v[170:171] op_sel:[1,1] op_sel_hi:[1,0]
	v_pk_mul_f32 v[40:41], v[6:7], v[170:171]
	v_pk_fma_f32 v[6:7], v[6:7], v[170:171], v[42:43] op_sel_hi:[0,1,1]
	v_sub_f32_e32 v6, v40, v42
.LBB0_1296:
	v_pk_mul_f32 v[10:11], v[18:19], v[10:11]
	s_and_b64 vcc, exec, s[0:1]
	v_pk_mul_f32 v[10:11], v[10:11], v[204:205]
	s_cbranch_vccnz .LBB0_1298
	v_pk_mul_f32 v[42:43], v[10:11], v[172:173] op_sel:[1,1] op_sel_hi:[1,0]
	v_pk_mul_f32 v[40:41], v[10:11], v[172:173]
	v_pk_fma_f32 v[10:11], v[10:11], v[172:173], v[42:43] op_sel_hi:[0,1,1]
	v_sub_f32_e32 v10, v40, v42
.LBB0_1298:
	v_pk_mul_f32 v[16:17], v[18:19], v[16:17]
	s_and_b64 vcc, exec, s[0:1]
	v_pk_mul_f32 v[16:17], v[16:17], v[206:207]
	s_cbranch_vccnz .LBB0_1300
	v_pk_mul_f32 v[42:43], v[16:17], v[174:175] op_sel:[1,1] op_sel_hi:[1,0]
	v_pk_mul_f32 v[40:41], v[16:17], v[174:175]
	v_pk_fma_f32 v[16:17], v[16:17], v[174:175], v[42:43] op_sel_hi:[0,1,1]
	v_sub_f32_e32 v16, v40, v42
.LBB0_1300:
	v_pk_mul_f32 v[22:23], v[18:19], v[22:23]
	s_and_b64 vcc, exec, s[0:1]
	v_pk_mul_f32 v[22:23], v[22:23], v[208:209]
	s_cbranch_vccnz .LBB0_1302
	v_pk_mul_f32 v[42:43], v[22:23], v[176:177] op_sel:[1,1] op_sel_hi:[1,0]
	v_pk_mul_f32 v[40:41], v[22:23], v[176:177]
	v_pk_fma_f32 v[22:23], v[22:23], v[176:177], v[42:43] op_sel_hi:[0,1,1]
	v_sub_f32_e32 v22, v40, v42
.LBB0_1302:
	v_pk_mul_f32 v[26:27], v[18:19], v[26:27]
	s_and_b64 vcc, exec, s[0:1]
	v_pk_mul_f32 v[26:27], v[26:27], v[210:211]
	s_cbranch_vccnz .LBB0_1304
	v_pk_mul_f32 v[42:43], v[26:27], v[178:179] op_sel:[1,1] op_sel_hi:[1,0]
	v_pk_mul_f32 v[40:41], v[26:27], v[178:179]
	v_pk_fma_f32 v[26:27], v[26:27], v[178:179], v[42:43] op_sel_hi:[0,1,1]
	v_sub_f32_e32 v26, v40, v42
.LBB0_1304:
	v_pk_mul_f32 v[30:31], v[18:19], v[30:31]
	s_and_b64 vcc, exec, s[0:1]
	v_pk_mul_f32 v[30:31], v[30:31], v[212:213]
	s_cbranch_vccnz .LBB0_1306
	v_pk_mul_f32 v[42:43], v[30:31], v[180:181] op_sel:[1,1] op_sel_hi:[1,0]
	v_pk_mul_f32 v[40:41], v[30:31], v[180:181]
	v_pk_fma_f32 v[30:31], v[30:31], v[180:181], v[42:43] op_sel_hi:[0,1,1]
	v_sub_f32_e32 v30, v40, v42
.LBB0_1306:
	v_pk_mul_f32 v[34:35], v[18:19], v[34:35]
	s_and_b64 vcc, exec, s[0:1]
	v_pk_mul_f32 v[34:35], v[34:35], v[214:215]
	s_cbranch_vccnz .LBB0_1308
	v_pk_mul_f32 v[42:43], v[34:35], v[182:183] op_sel:[1,1] op_sel_hi:[1,0]
	v_pk_mul_f32 v[40:41], v[34:35], v[182:183]
	v_pk_fma_f32 v[34:35], v[34:35], v[182:183], v[42:43] op_sel_hi:[0,1,1]
	v_sub_f32_e32 v34, v40, v42
.LBB0_1308:
	v_pk_mul_f32 v[36:37], v[18:19], v[36:37]
	s_and_b64 vcc, exec, s[0:1]
	v_pk_mul_f32 v[36:37], v[36:37], v[216:217]
	s_cbranch_vccnz .LBB0_1310
	v_pk_mul_f32 v[42:43], v[36:37], v[184:185] op_sel:[1,1] op_sel_hi:[1,0]
	v_pk_mul_f32 v[40:41], v[36:37], v[184:185]
	v_pk_fma_f32 v[36:37], v[36:37], v[184:185], v[42:43] op_sel_hi:[0,1,1]
	v_sub_f32_e32 v36, v40, v42
.LBB0_1310:
	v_pk_mul_f32 v[32:33], v[18:19], v[32:33]
	s_and_b64 vcc, exec, s[0:1]
	v_pk_mul_f32 v[32:33], v[32:33], v[218:219]
	s_cbranch_vccnz .LBB0_1312
	v_pk_mul_f32 v[42:43], v[32:33], v[186:187] op_sel:[1,1] op_sel_hi:[1,0]
	v_pk_mul_f32 v[40:41], v[32:33], v[186:187]
	v_pk_fma_f32 v[32:33], v[32:33], v[186:187], v[42:43] op_sel_hi:[0,1,1]
	v_sub_f32_e32 v32, v40, v42
.LBB0_1312:
	v_pk_mul_f32 v[28:29], v[18:19], v[28:29]
	s_and_b64 vcc, exec, s[0:1]
	v_pk_mul_f32 v[28:29], v[28:29], v[220:221]
	s_cbranch_vccnz .LBB0_1314
	v_pk_mul_f32 v[42:43], v[28:29], v[188:189] op_sel:[1,1] op_sel_hi:[1,0]
	v_pk_mul_f32 v[40:41], v[28:29], v[188:189]
	v_pk_fma_f32 v[28:29], v[28:29], v[188:189], v[42:43] op_sel_hi:[0,1,1]
	v_sub_f32_e32 v28, v40, v42
.LBB0_1314:
	v_pk_mul_f32 v[24:25], v[18:19], v[24:25]
	s_and_b64 vcc, exec, s[0:1]
	v_pk_mul_f32 v[24:25], v[24:25], v[222:223]
	s_cbranch_vccnz .LBB0_1316
	v_pk_mul_f32 v[42:43], v[24:25], v[190:191] op_sel:[1,1] op_sel_hi:[1,0]
	v_pk_mul_f32 v[40:41], v[24:25], v[190:191]
	v_pk_fma_f32 v[24:25], v[24:25], v[190:191], v[42:43] op_sel_hi:[0,1,1]
	v_sub_f32_e32 v24, v40, v42
.LBB0_1316:
	v_pk_mul_f32 v[20:21], v[18:19], v[20:21]
	s_and_b64 vcc, exec, s[0:1]
	v_pk_mul_f32 v[20:21], v[20:21], v[224:225]
	s_cbranch_vccnz .LBB0_1318
	v_pk_mul_f32 v[42:43], v[20:21], v[192:193] op_sel:[1,1] op_sel_hi:[1,0]
	v_pk_mul_f32 v[40:41], v[20:21], v[192:193]
	v_pk_fma_f32 v[20:21], v[20:21], v[192:193], v[42:43] op_sel_hi:[0,1,1]
	v_sub_f32_e32 v20, v40, v42
.LBB0_1318:
	v_pk_mul_f32 v[12:13], v[18:19], v[12:13]
	s_and_b64 vcc, exec, s[0:1]
	v_pk_mul_f32 v[12:13], v[12:13], v[226:227]
	s_cbranch_vccnz .LBB0_1320
	v_pk_mul_f32 v[42:43], v[12:13], v[194:195] op_sel:[1,1] op_sel_hi:[1,0]
	v_pk_mul_f32 v[40:41], v[12:13], v[194:195]
	v_pk_fma_f32 v[12:13], v[12:13], v[194:195], v[42:43] op_sel_hi:[0,1,1]
	v_sub_f32_e32 v12, v40, v42
.LBB0_1320:
	v_pk_mul_f32 v[8:9], v[18:19], v[8:9]
	s_and_b64 vcc, exec, s[0:1]
	v_pk_mul_f32 v[8:9], v[8:9], v[228:229]
	s_cbranch_vccnz .LBB0_1322
	v_pk_mul_f32 v[42:43], v[8:9], v[196:197] op_sel:[1,1] op_sel_hi:[1,0]
	v_pk_mul_f32 v[40:41], v[8:9], v[196:197]
	v_pk_fma_f32 v[8:9], v[8:9], v[196:197], v[42:43] op_sel_hi:[0,1,1]
	v_sub_f32_e32 v8, v40, v42
.LBB0_1322:
	v_pk_mul_f32 v[0:1], v[18:19], v[4:5]
	s_and_b64 vcc, exec, s[0:1]
	v_pk_mul_f32 v[0:1], v[0:1], v[246:247]
	s_cbranch_vccnz .LBB0_1325
	s_mov_b32 s14, 34
	v_pk_mul_f32 v[18:19], v[0:1], v[198:199] op_sel:[1,1] op_sel_hi:[1,0]
	v_pk_mul_f32 v[14:15], v[0:1], v[198:199]
	v_pk_fma_f32 v[0:1], v[0:1], v[198:199], v[18:19] op_sel_hi:[0,1,1]
	v_sub_f32_e32 v0, v14, v18
	s_branch .LBB0_1326

; #define OPAQUE_IDS int tx = threadIdx.x; int bx = blockIdx.x; asm volatile("" : "+v"(tx), "+s"(bx));
; DI void hgrn_scan_mfma(const Params& p, char* shm) {
;     OPAQUE_IDS
;     constexpr int C = 32, QS = 272;
;     const unsigned char* P = p.ws + WS_P;
;     const bf16_t* V = (const bf16_t*)(P + P_HV); const float* EB = (const float*)(p.ws + WS_EB); const bf16_t* Qh = (const bf16_t*)(P + P_HQ);
;     char* QtL = shm;
;     char* VL = QtL + C * QS;
;     char* KtL = VL + C * QS;
;     float* eBL = (float*)(KtL + C * QS);
;     const int tid = tx, w = tid >> 6, lane = tid & 63, l15 = lane & 15, g = lane >> 4;
;     for (int u = bx; u < 128; u += gridDim.x) {
;         const int dir = u & 1, head = (u >> 1) & 7, b = u >> 4;
;         const unsigned char* Fb = P + (dir ? P_HF1 : P_HF0); bf16_t* Oo = dir ? (bf16_t*)(p.ws + WS_P + P_HOB) : (bf16_t*)(p.ws + WS_H);
;         f32x4 S[8];
; #pragma unroll
;         for (int kt = 0; kt < 8; ++kt) S[kt] = (f32x4){0.f, 0.f, 0.f, 0.f};
;         const int lt = tid >> 4, lp = tid & 15;
;         u32x4 ra0, ra1, ra2, ra3, ra4, rb0, rb1, rb2, rb3, rb4;
;     ...
;         HG_LOAD(0, ra0, ra1, ra2, ra3, ra4); HG_LOAD(1, rb0, rb1, rb2, rb3, rb4);
.LBB0_2409:
	s_or_b64 exec, exec, s[0:1]
	s_mov_b32 s46, s87
	s_waitcnt lgkmcnt(0)
	v_mov_b32_e32 v0, v252
	s_barrier
	s_lshr_b32 s99, s46, 7
	s_and_b32 s46, s46, 0x7f
	v_readfirstlane_b32 s100, v252
	s_nop 3
	s_lshr_b32 s100, s100, 8
	s_cmpk_gt_i32 s46, 0x7f
	s_cbranch_scc1 .LBB0_2443
	s_add_u32 s36, s68, 0xfeda000
	v_and_b32_e32 v1, 15, v0
	v_mov_b32_e32 v2, 0
	s_addc_u32 s37, s69, 0
	v_lshlrev_b32_e32 v4, 4, v1
	v_mov_b32_e32 v5, v2
	v_bfe_u32 v3, v0, 4, 2
	v_lshl_add_u64 v[116:117], s[96:97], 0, v[4:5]
	v_lshl_add_u64 v[118:119], s[36:37], 0, v[4:5]
	v_ashrrev_i32_e32 v5, 2, v0
	v_ashrrev_i32_e32 v113, 4, v0
	v_bfi_b32 v120, -16, v5, v0
	v_lshl_add_u32 v120, s99, 6, v120
	v_mul_u32_u24_e32 v5, 0x220, v3
	s_movk_i32 s47, 0xff
	v_cmp_gt_i32_e64 s[2:3], 32, v0
	v_lshlrev_b32_e32 v114, 2, v0
	v_lshl_add_u32 v5, v5, 1, 0
	s_movk_i32 s0, 0x110
	s_movk_i32 s1, 0xfbd0
	v_lshlrev_b32_e32 v9, 4, v0
	v_mov_b32_e32 v0, 0xff
	v_mov_b32_e32 v10, 0x9ff
	v_cmp_lt_i32_e32 vcc, s47, v113
	v_lshl_add_u32 v148, v120, 1, v5
	v_mad_u32_u24 v6, v1, s0, 0
	v_mad_i32_i24 v149, v3, s1, v5
	v_mul_lo_u32 v5, v113, s0
	v_cndmask_b32_e32 v0, v0, v10, vcc
	s_movk_i32 s0, 0xdf
	v_sub_u32_e32 v150, v0, v113
	v_mov_b32_e32 v0, 0xdf
	v_mov_b32_e32 v10, 0x9df
	v_cmp_lt_i32_e32 vcc, s0, v113
	v_lshlrev_b32_e32 v147, 2, v3
	v_ashrrev_i32_e32 v115, 31, v114
	v_cndmask_b32_e32 v0, v0, v10, vcc
	v_lshlrev_b32_e32 v7, 4, v3
	v_lshlrev_b32_e32 v8, 3, v3
	v_mul_u32_u24_e32 v3, 0x430, v3
	v_sub_u32_e32 v151, v0, v113
	v_or_b32_e32 v153, 2, v147
	v_or_b32_e32 v154, 3, v147
	v_lshlrev_b32_e32 v0, 1, v1
	s_bitcmp1_b32 s46, 0
	v_lshlrev_b32_e32 v112, 3, v1
	v_cmp_gt_u32_e64 s[4:5], v147, v1
	v_cmp_lt_u32_e64 s[6:7], v147, v1
	v_cmp_gt_u32_e64 s[8:9], v153, v1
	v_cmp_gt_u32_e64 s[10:11], v154, v1
	v_add3_u32 v155, v149, v3, v0
	v_lshl_add_u64 v[0:1], v[114:115], 2, s[68:69]
	s_mov_b64 s[0:1], 0x16ae1000
	s_cselect_b64 s[40:41], -1, 0
	s_bitcmp1_b32 s31, 0
	v_add_u32_e32 v5, 0, v5
	v_lshl_add_u64 v[122:123], v[0:1], 0, s[0:1]
	s_cselect_b64 s[0:1], -1, 0
	v_lshlrev_b32_e32 v124, 1, v112
	v_add_u32_e32 v146, 32, v113
	s_mov_b32 s39, 0
	v_ashrrev_i32_e32 v121, 31, v120
	s_movk_i32 s58, 0x9ff
	v_or_b32_e32 v152, 1, v147
	s_xor_b64 s[42:43], s[12:13], s[0:1]
	s_lshl_b32 s31, s46, 6
	s_lshl_b32 s59, s26, 6
	v_sub_u32_e32 v156, 0, v113
	s_mov_b32 s71, 0x2400000
	v_mov_b32_e32 v157, 0x900
	v_mov_b32_e32 v126, v124
	v_mov_b32_e32 v127, v2
	s_mov_b32 s72, 0x26da000
	s_movk_i32 s73, 0x400
	s_mov_b64 s[44:45], 0x2000
	v_add_u32_e32 v158, v5, v4
	v_add_u32_e32 v159, 0, v9
	v_add_u32_e32 v160, v6, v7
	v_add_u32_e32 v161, v6, v8
	s_branch .LBB0_2412

; DI void hgrn_scan_mfma(const Params& p, char* shm) {
;     ...
;     for (int u = bx; u < 128; u += gridDim.x) {
;         const int dir = u & 1, head = (u >> 1) & 7, b = u >> 4;
;         const unsigned char* Fb = P + (dir ? P_HF1 : P_HF0); bf16_t* Oo = dir ? (bf16_t*)(p.ws + WS_P + P_HOB) : (bf16_t*)(p.ws + WS_H);
;         f32x4 S[8];
; #pragma unroll
;         for (int kt = 0; kt < 8; ++kt) S[kt] = (f32x4){0.f, 0.f, 0.f, 0.f};
;         const int lt = tid >> 4, lp = tid & 15;
;         u32x4 ra0, ra1, ra2, ra3, ra4, rb0, rb1, rb2, rb3, rb4;
;     ...
;         HG_LOAD(0, ra0, ra1, ra2, ra3, ra4); HG_LOAD(1, rb0, rb1, rb2, rb3, rb4);
.LBB0_2416:
	s_or_b64 exec, exec, s[14:15]
	v_cndmask_b32_e64 v3, 0, 1, s[40:41]
	v_lshl_add_u64 v[142:143], s[0:1], 0, v[0:1]
	v_readfirstlane_b32 s14, v3
	s_lshl_b32 s55, s14, 3
	s_lshl_b32 s14, s31, 2
	s_and_b32 s56, s14, 0xe00
	s_and_b64 s[14:15], s[12:13], exec
	s_cselect_b32 s14, s72, 0x146da000
	s_add_u32 s14, s68, s14
	s_addc_u32 s15, s69, 0
	s_add_u32 s14, s14, s38
	s_addc_u32 s15, s15, 0
	v_lshl_add_u64 v[132:133], v[120:121], 1, s[14:15]
	s_and_b64 s[14:15], s[12:13], exec
	s_cselect_b32 s15, 0, -1
	s_cselect_b32 s14, s73, 0xfffffc00
	s_add_i32 s0, s54, s55
	s_mul_hi_i32 s1, s0, 0x48000
	s_mul_i32 s0, s0, 0x48000
	s_or_b32 s0, s0, s56
	v_mov_b32_e32 v44, 0
	s_mov_b32 s74, 0
	v_lshl_add_u64 v[128:129], v[116:117], 0, s[38:39]
	v_lshl_add_u64 v[130:131], v[118:119], 0, s[38:39]
	v_mul_hi_i32_i24_e32 v135, s14, v147
	v_mul_i32_i24_e32 v134, s14, v147
	s_lshl_b64 s[52:53], s[14:15], 5
	v_mul_hi_i32_i24_e32 v137, s14, v152
	v_mul_i32_i24_e32 v136, s14, v152
	v_mul_hi_i32_i24_e32 v139, s14, v153
	v_mul_i32_i24_e32 v138, s14, v153
	v_mul_hi_i32_i24_e32 v141, s14, v154
	v_mul_i32_i24_e32 v140, s14, v154
	v_lshl_add_u64 v[144:145], v[122:123], 0, s[0:1]
	s_movk_i32 s38, 0xffe0
	s_mov_b32 s76, 0
	v_mov_b32_e32 v45, v44
	v_mov_b32_e32 v46, v44
	v_mov_b32_e32 v47, v44
	v_mov_b32_e32 v48, v44
	v_mov_b32_e32 v49, v44
	v_mov_b32_e32 v50, v44
	v_mov_b32_e32 v51, v44
	v_mov_b32_e32 v52, v44
	v_mov_b32_e32 v53, v44
	v_mov_b32_e32 v54, v44
	v_mov_b32_e32 v55, v44
	v_mov_b32_e32 v56, v44
	v_mov_b32_e32 v57, v44
	v_mov_b32_e32 v58, v44
	v_mov_b32_e32 v59, v44
	v_mov_b32_e32 v60, v44
	v_mov_b32_e32 v61, v44
	v_mov_b32_e32 v62, v44
	v_mov_b32_e32 v63, v44
	v_mov_b32_e32 v64, v44
	v_mov_b32_e32 v65, v44
	v_mov_b32_e32 v66, v44
	v_mov_b32_e32 v67, v44
	v_mov_b32_e32 v72, v44
	v_mov_b32_e32 v73, v44
	v_mov_b32_e32 v74, v44
	v_mov_b32_e32 v75, v44
	v_mov_b32_e32 v68, v44
	v_mov_b32_e32 v69, v44
	v_mov_b32_e32 v70, v44
	v_mov_b32_e32 v71, v44
	s_cmp_lg_u32 s100, 0
	s_cbranch_scc1 .Lscanh_2417

; DI unsigned pack2(float lo, float hi) { const f32x2 v = (f32x2){lo, hi}; return __builtin_bit_cast(unsigned, __builtin_convertvector(v, bf16x2_t)); }
; DI void hgrn_scan_mfma(const Params& p, char* shm) {
;     ...
;             { const bf16_t* kt16 = (const bf16_t*)KtL; const bf16_t* v16 = (const bf16_t*)VL; const int vcol = w * 16 + l15;
;     ...
;               const bf16x8 vf = __builtin_bit_cast(bf16x8, (u32x4){HG_U2(v16, g * 4 + 0, g * 4 + 1, vcol), HG_U2(v16, g * 4 + 2, g * 4 + 3, vcol), HG_U2(v16, 16 + g * 4 + 0, 16 + g * 4 + 1, vcol), HG_U2(v16, 16 + g * 4 + 2, 16 + g * 4 + 3, vcol)});
;               f32x4 sc00 = (f32x4){0.f, 0.f, 0.f, 0.f}, sc01 = sc00, sc11 = sc00, o0 = sc00, o1 = sc00;
; #pragma unroll
;               for (int kc = 0; kc < 4; ++kc) {
;                   const bf16x8 aK0 = *(const bf16x8*)(KtL + l15 * QS + kc * 64 + g * 16), aK1 = *(const bf16x8*)(KtL + (16 + l15) * QS + kc * 64 + g * 16);
;                   const bf16x8 bQ0 = *(const bf16x8*)(QtL + l15 * QS + kc * 64 + g * 16), bQ1 = *(const bf16x8*)(QtL + (16 + l15) * QS + kc * 64 + g * 16);
;                   sc00 = __builtin_amdgcn_mfma_f32_16x16x32_bf16(aK0, bQ0, sc00, 0, 0, 0);
;                   sc01 = __builtin_amdgcn_mfma_f32_16x16x32_bf16(aK0, bQ1, sc01, 0, 0, 0);
;                   sc11 = __builtin_amdgcn_mfma_f32_16x16x32_bf16(aK1, bQ1, sc11, 0, 0, 0);
;                   const int kp = kc;
;                   const u32x2 qa0 = *(const u32x2*)(QtL + l15 * QS + ((2 * kp) * 16 + g * 4) * 2), qb0 = *(const u32x2*)(QtL + l15 * QS + ((2 * kp + 1) * 16 + g * 4) * 2);
;                   const u32x2 qa1 = *(const u32x2*)(QtL + (16 + l15) * QS + ((2 * kp) * 16 + g * 4) * 2), qb1 = *(const u32x2*)(QtL + (16 + l15) * QS + ((2 * kp + 1) * 16 + g * 4) * 2);
;                   const bf16x8 sw = __builtin_bit_cast(bf16x8, (u32x4){pack2(S[2 * kp][0], S[2 * kp][1]), pack2(S[2 * kp][2], S[2 * kp][3]), pack2(S[2 * kp + 1][0], S[2 * kp + 1][1]), pack2(S[2 * kp + 1][2], S[2 * kp + 1][3])});
;                   o0 = __builtin_amdgcn_mfma_f32_16x16x32_bf16(__builtin_bit_cast(bf16x8, (u32x4){qa0.x, qa0.y, qb0.x, qb0.y}), sw, o0, 0, 0, 0);
;                   o1 = __builtin_amdgcn_mfma_f32_16x16x32_bf16(__builtin_bit_cast(bf16x8, (u32x4){qa1.x, qa1.y, qb1.x, qb1.y}), sw, o1, 0, 0, 0); }
; #pragma unroll
;               for (int r = 0; r < 4; ++r) if (g * 4 + r > l15) { sc00[r] = 0.f; sc11[r] = 0.f; }
.LBB0_2441:
	v_pk_mul_f32 v[58:59], v[98:99], v[58:59]
	v_pk_mul_f32 v[56:57], v[96:97], v[56:57]
	ds_read_b128 v[96:99], v160 offset:17408
	v_pk_mul_f32 v[62:63], v[94:95], v[62:63]
	v_pk_mul_f32 v[60:61], v[92:93], v[60:61]
	ds_read_b128 v[68:71], v160 offset:21760
	ds_read_b128 v[92:95], v160
	v_pk_mul_f32 v[46:47], v[110:111], v[46:47]
	v_pk_mul_f32 v[44:45], v[108:109], v[44:45]
	v_pk_mul_f32 v[50:51], v[106:107], v[50:51]
	v_pk_mul_f32 v[48:49], v[104:105], v[48:49]
	v_pk_mul_f32 v[54:55], v[102:103], v[54:55]
	v_pk_mul_f32 v[52:53], v[100:101], v[52:53]
	ds_read_b128 v[100:103], v160 offset:4352
	ds_read_b128 v[104:107], v160 offset:17472
	ds_read_b128 v[108:111], v160 offset:64
	ds_read_b128 v[162:165], v160 offset:21824
	ds_read_b128 v[166:169], v160 offset:4416
	v_pk_mul_f32 v[66:67], v[90:91], v[66:67]
	s_waitcnt lgkmcnt(5)
	v_mfma_f32_16x16x32_bf16 v[90:93], v[96:99], v[92:95], 0
	v_mul_f32_e64 v64, v88, v64
	v_mul_f32_e64 v65, v89, v65
	v_pk_mul_f32 v[78:79], v[74:75], v[78:79]
	v_pk_mul_f32 v[76:77], v[72:73], v[76:77]
	s_waitcnt lgkmcnt(4)
	v_mfma_f32_16x16x32_bf16 v[170:173], v[68:71], v[100:103], 0
	v_mul_f32_e64 v70, v86, v82
	v_mul_f32_e64 v71, v87, v83
	v_pk_mul_f32 v[68:69], v[84:85], v[80:81]
	ds_read_b128 v[84:87], v160 offset:17536
	s_waitcnt lgkmcnt(3)
	v_mfma_f32_16x16x32_bf16 v[80:83], v[104:107], v[108:111], v[90:93]
	s_nop 2
	ds_read_b128 v[88:91], v160 offset:21888
	ds_read_b128 v[92:95], v160 offset:128
	v_cvt_pk_bf16_f32 v186, v52, v53
	v_cvt_pk_bf16_f32 v187, v54, v55
	s_waitcnt lgkmcnt(3)
	v_mfma_f32_16x16x32_bf16 v[108:111], v[162:165], v[166:169], v[170:173]
	ds_read_b128 v[162:165], v160 offset:4480
	s_nop 1
	ds_read_b128 v[170:173], v160 offset:17600
	ds_read_b128 v[174:177], v160 offset:192
	ds_read_b128 v[72:75], v160 offset:21952
	ds_read_b128 v[178:181], v160 offset:4544
	v_cvt_pk_bf16_f32 v188, v56, v57
	s_waitcnt lgkmcnt(4)
	v_mfma_f32_16x16x32_bf16 v[88:91], v[88:91], v[162:165], v[108:111]
	v_cvt_pk_bf16_f32 v189, v58, v59
	s_add_i32 s14, s74, 32
	s_and_b64 s[0:1], s[12:13], exec
	v_mfma_f32_16x16x32_bf16 v[92:95], v[84:87], v[92:95], v[80:83]
	ds_read_u16 v0, v148 offset:8704
	ds_read_u16 v1, v148 offset:8976
	ds_read_u16 v3, v148 offset:9248
	ds_read_u16 v81, v148 offset:9520
	ds_read_u16 v82, v148 offset:13056
	ds_read_u16 v83, v148 offset:13328
	ds_read_u16 v182, v148 offset:13600
	ds_read_u16 v183, v148 offset:13872
	ds_read2_b64 v[108:111], v161 offset1:4
	s_waitcnt lgkmcnt(7)
	v_lshl_or_b32 v80, v1, 16, v0
	v_mfma_f32_16x16x32_bf16 v[72:75], v[72:75], v[178:181], v[88:91]
	s_waitcnt lgkmcnt(3)
	v_lshl_or_b32 v82, v83, 16, v82
	s_waitcnt lgkmcnt(1)
	v_lshl_or_b32 v83, v183, 16, v182
	v_mov_b32_e32 v0, s39
	ds_read2_b64 v[88:91], v125 offset0:32 offset1:36
	v_mfma_f32_16x16x32_bf16 v[96:99], v[96:99], v[100:103], 0
	v_lshl_or_b32 v81, v81, 16, v3
	s_cselect_b32 s0, s14, s77
	s_add_u32 s0, s50, s0
	v_mfma_f32_16x16x32_bf16 v[92:95], v[170:173], v[174:177], v[92:95]
	v_cvt_pk_bf16_f32 v174, v44, v45
	v_cvt_pk_bf16_f32 v175, v46, v47
	v_cvt_pk_bf16_f32 v176, v48, v49
	v_cvt_pk_bf16_f32 v177, v50, v51
	v_mfma_f32_16x16x32_bf16 v[96:99], v[104:107], v[166:169], v[96:99]
	s_nop 2
	v_cndmask_b32_e64 v0, v92, v0, s[4:5]
	v_cndmask_b32_e64 v0, v0, v92, s[6:7]
	v_cndmask_b32_e64 v3, v94, 0, s[8:9]
	s_waitcnt lgkmcnt(1)
	v_mfma_f32_16x16x32_bf16 v[100:103], v[108:111], v[174:177], 0
	ds_read2_b64 v[108:111], v161 offset0:8 offset1:12
	ds_read2_b64 v[182:185], v125 offset0:40 offset1:44
	ds_read2_b64 v[104:107], v161 offset0:16 offset1:20
	ds_read2_b64 v[166:169], v125 offset0:48 offset1:52
	s_addc_u32 s1, s51, 0
	s_waitcnt lgkmcnt(4)
	v_mfma_f32_16x16x32_bf16 v[88:91], v[88:91], v[174:177], 0
	v_cvt_pk_bf16_f32 v174, v60, v61
	v_cvt_pk_bf16_f32 v175, v62, v63
	v_cvt_pk_bf16_f32 v176, v64, v65
	s_waitcnt lgkmcnt(3)
	v_mfma_f32_16x16x32_bf16 v[100:103], v[108:111], v[186:189], v[100:103]
	v_cvt_pk_bf16_f32 v177, v66, v67
	s_lshl_b64 s[0:1], s[0:1], 11
	v_lshl_add_u64 v[144:145], v[144:145], 0, s[44:45]
	v_mfma_f32_16x16x32_bf16 v[84:87], v[84:87], v[162:165], v[96:99]
	s_sub_i32 s38, s38, 64
	s_add_i32 s74, s74, 64
	s_and_b64 vcc, exec, s[54:55]
	s_waitcnt lgkmcnt(2)
	v_mfma_f32_16x16x32_bf16 v[88:91], v[182:185], v[186:189], v[88:91]
	ds_read2_b64 v[108:111], v161 offset0:24 offset1:28
	ds_read2_b64 v[182:185], v125 offset0:56 offset1:60
	v_cvt_pk_bf16_f32 v186, v68, v69
	v_cvt_pk_bf16_f32 v187, v70, v71
	s_waitcnt lgkmcnt(3)
	v_mfma_f32_16x16x32_bf16 v[96:99], v[104:107], v[174:177], v[100:103]
	v_cvt_pk_bf16_f32 v188, v76, v77
	v_cvt_pk_bf16_f32 v189, v78, v79
	s_nop 0
	v_mov_b32_e32 v100, s39
	v_mfma_f32_16x16x32_bf16 v[84:87], v[170:173], v[178:181], v[84:87]
	v_cndmask_b32_e64 v1, v72, v100, s[4:5]
	v_cndmask_b32_e64 v100, v1, v72, s[6:7]
	v_cndmask_b32_e64 v1, 0, v93, s[6:7]
	s_waitcnt lgkmcnt(2)
	v_mfma_f32_16x16x32_bf16 v[88:91], v[166:169], v[174:177], v[88:91]
	v_cndmask_b32_e64 v72, v95, 0, s[10:11]
	v_cvt_pk_bf16_f32 v0, v0, v1
	v_cvt_pk_bf16_f32 v1, v3, v72
	s_waitcnt lgkmcnt(1)
	v_mfma_f32_16x16x32_bf16 v[92:95], v[108:111], v[186:189], v[96:99]
	v_mov_b32_e32 v3, v2
	v_cvt_pk_bf16_f32 v84, v84, v85
	v_cvt_pk_bf16_f32 v85, v86, v87
	v_cndmask_b32_e64 v96, 0, v73, s[6:7]
	v_cndmask_b32_e64 v97, v74, 0, s[8:9]
	v_cndmask_b32_e64 v98, v75, 0, s[10:11]
	v_cvt_pk_bf16_f32 v86, v100, v96
	v_cvt_pk_bf16_f32 v87, v97, v98
	s_waitcnt lgkmcnt(0)
; DI unsigned pack2(float lo, float hi) { const f32x2 v = (f32x2){lo, hi}; return __builtin_bit_cast(unsigned, __builtin_convertvector(v, bf16x2_t)); }
; DI void hgrn_scan_mfma(const Params& p, char* shm) {
;     ...
; #pragma unroll
;               for (int r = 0; r < 4; ++r) {
;                   const long rb_ = (long)HG_ROW(b, dir, ch * C), st_ = dir ? -(long)D : (long)D; bf16_t* op_ = Oo + rb_ * D + head * 128 + vcol + (long)(g * 4 + r) * st_;
;                   op_[0] = (bf16_t)(pack2(o0[r], 0.f) & 0xffffu); op_[16 * st_] = (bf16_t)(pack2(o1[r], 0.f) & 0xffffu); }
; #pragma unroll
;               for (int kt = 0; kt < 8; ++kt) { const f32x4 dcy = *(const f32x4*)(eBL + kt * 16 + g * 4); const int kcol = kt * 16 + l15;
;                   const bf16x8 kl = __builtin_bit_cast(bf16x8, (u32x4){HG_U2(kt16, g * 4 + 0, g * 4 + 1, kcol), HG_U2(kt16, g * 4 + 2, g * 4 + 3, kcol), HG_U2(kt16, 16 + g * 4 + 0, 16 + g * 4 + 1, kcol), HG_U2(kt16, 16 + g * 4 + 2, 16 + g * 4 + 3, kcol)});
;                   S[kt] = __builtin_amdgcn_mfma_f32_16x16x32_bf16(kl, vf, S[kt], 0, 0, 0) * dcy; }
	v_mfma_f32_16x16x32_bf16 v[88:91], v[182:185], v[186:189], v[88:91]
	v_mfma_f32_16x16x32_bf16 v[72:75], v[0:3], v[80:83], v[92:95]
	v_lshl_add_u64 v[0:1], v[132:133], 0, s[0:1]
	v_mfma_f32_16x16x32_bf16 v[84:87], v[84:87], v[80:83], v[88:91]
	s_nop 4
	v_lshl_add_u64 v[88:89], v[134:135], 1, v[0:1]
	v_cvt_pk_bf16_f32 v3, v72, s0
	global_store_short v[88:89], v3, off
	v_cvt_pk_bf16_f32 v3, v84, s0
	v_lshl_add_u64 v[88:89], v[88:89], 0, s[52:53]
	global_store_short v[88:89], v3, off
	v_lshl_add_u64 v[88:89], v[136:137], 1, v[0:1]
	v_cvt_pk_bf16_f32 v3, v73, s0
	global_store_short v[88:89], v3, off
	v_cvt_pk_bf16_f32 v3, v85, s0
	v_lshl_add_u64 v[72:73], v[88:89], 0, s[52:53]
	global_store_short v[72:73], v3, off
	v_lshl_add_u64 v[72:73], v[138:139], 1, v[0:1]
	v_cvt_pk_bf16_f32 v3, v74, s0
	global_store_short v[72:73], v3, off
	v_cvt_pk_bf16_f32 v3, v86, s0
	v_lshl_add_u64 v[72:73], v[72:73], 0, s[52:53]
	global_store_short v[72:73], v3, off
	v_lshl_add_u64 v[0:1], v[140:141], 1, v[0:1]
	v_cvt_pk_bf16_f32 v3, v75, s0
	global_store_short v[0:1], v3, off
	v_cvt_pk_bf16_f32 v3, v87, s0
	v_lshl_add_u64 v[0:1], v[0:1], 0, s[52:53]
	global_store_short v[0:1], v3, off
	ds_read_b128 v[72:75], v149 offset:26112
	ds_read_u16 v0, v155 offset:17408
	ds_read_u16 v1, v155 offset:17440
	ds_read_u16 v3, v155 offset:17472
	ds_read_u16 v92, v155 offset:17504
	ds_read_u16 v93, v155 offset:17536
	ds_read_u16 v94, v155 offset:17568
	ds_read_u16 v95, v155 offset:17600
	ds_read_u16 v96, v155 offset:17632
	ds_read_u16 v84, v155 offset:17680
	ds_read_u16 v88, v155 offset:17712
	ds_read_u16 v97, v155 offset:17744
	ds_read_u16 v98, v155 offset:17776
	ds_read_u16 v99, v155 offset:17808
	ds_read_u16 v100, v155 offset:17840
	ds_read_u16 v101, v155 offset:17872
	ds_read_u16 v102, v155 offset:17904
	s_waitcnt lgkmcnt(7)
	v_lshl_or_b32 v84, v84, 16, v0
	ds_read_u16 v0, v155 offset:17952
	ds_read_u16 v89, v155 offset:17984
	ds_read_u16 v103, v155 offset:18016
	ds_read_u16 v104, v155 offset:18048
	ds_read_u16 v105, v155 offset:18080
	ds_read_u16 v106, v155 offset:18112
	ds_read_u16 v107, v155 offset:18144
	ds_read_u16 v108, v155 offset:18176
	ds_read_u16 v85, v155 offset:18224
	ds_read_u16 v90, v155 offset:18256
	ds_read_u16 v109, v155 offset:18288
	ds_read_u16 v110, v155 offset:18320
	ds_read_u16 v111, v155 offset:18352
	ds_read_u16 v125, v155 offset:18384
	ds_read_u16 v162, v155 offset:18416
	ds_read_u16 v163, v155 offset:18448
	s_waitcnt lgkmcnt(7)
	v_lshl_or_b32 v85, v85, 16, v0
	ds_read_u16 v0, v155 offset:21760
	ds_read_u16 v91, v155 offset:21792
	ds_read_u16 v164, v155 offset:21824
	ds_read_u16 v165, v155 offset:21856
	ds_read_u16 v166, v155 offset:21888
	ds_read_u16 v167, v155 offset:21920
	ds_read_u16 v168, v155 offset:21952
	ds_read_u16 v169, v155 offset:21984
	ds_read_u16 v86, v155 offset:22032
	ds_read_u16 v170, v155 offset:22064
	ds_read_u16 v171, v155 offset:22096
	ds_read_u16 v172, v155 offset:22128
	ds_read_u16 v173, v155 offset:22160
	ds_read_u16 v174, v155 offset:22192
	ds_read_u16 v175, v155 offset:22224
	ds_read_u16 v176, v155 offset:22256
	s_waitcnt lgkmcnt(7)
	v_lshl_or_b32 v86, v86, 16, v0
	ds_read_u16 v0, v155 offset:22304
	ds_read_u16 v177, v155 offset:22336
	ds_read_u16 v178, v155 offset:22368
	ds_read_u16 v179, v155 offset:22400
	ds_read_u16 v180, v155 offset:22432
	ds_read_u16 v181, v155 offset:22464
	ds_read_u16 v182, v155 offset:22496
	ds_read_u16 v183, v155 offset:22528
	ds_read_u16 v87, v155 offset:22576
	ds_read_u16 v184, v155 offset:22608
	ds_read_u16 v185, v155 offset:22640
	ds_read_u16 v186, v155 offset:22672
	ds_read_u16 v187, v155 offset:22704
	ds_read_u16 v188, v155 offset:22736
	ds_read_u16 v189, v155 offset:22768
	ds_read_u16 v190, v155 offset:22800
	s_waitcnt lgkmcnt(7)
	v_lshl_or_b32 v87, v87, 16, v0
	v_lshl_or_b32 v88, v88, 16, v1
	v_lshl_or_b32 v89, v90, 16, v89
	v_lshl_or_b32 v90, v170, 16, v91
	s_waitcnt lgkmcnt(6)
	v_lshl_or_b32 v91, v184, 16, v177
	v_mfma_f32_16x16x32_bf16 v[44:47], v[84:87], v[80:83], v[44:47]
	ds_read_b128 v[84:87], v149 offset:26176
	v_mfma_f32_16x16x32_bf16 v[48:51], v[88:91], v[80:83], v[48:51]
	v_lshl_or_b32 v88, v98, 16, v92
	s_nop 4
	v_pk_mul_f32 v[46:47], v[74:75], v[46:47]
	v_pk_mul_f32 v[44:45], v[72:73], v[44:45]
	ds_read_b128 v[72:75], v149 offset:26240
	v_lshl_or_b32 v89, v110, 16, v104
	s_waitcnt lgkmcnt(1)
	v_pk_mul_f32 v[50:51], v[86:87], v[50:51]
	v_pk_mul_f32 v[48:49], v[84:85], v[48:49]
	v_lshl_or_b32 v84, v97, 16, v3
	v_lshl_or_b32 v85, v109, 16, v103
	v_lshl_or_b32 v86, v171, 16, v164
	v_lshl_or_b32 v87, v185, 16, v178
	v_lshl_or_b32 v90, v172, 16, v165
	v_lshl_or_b32 v91, v186, 16, v179
	v_mfma_f32_16x16x32_bf16 v[52:55], v[84:87], v[80:83], v[52:55]
	ds_read_b128 v[84:87], v149 offset:26304
	v_mfma_f32_16x16x32_bf16 v[56:59], v[88:91], v[80:83], v[56:59]
	s_waitcnt lgkmcnt(1)
	s_nop 4
	v_pk_mul_f32 v[54:55], v[74:75], v[54:55]
	v_pk_mul_f32 v[52:53], v[72:73], v[52:53]
	ds_read_b128 v[72:75], v149 offset:26368
	v_lshl_or_b32 v88, v100, 16, v94
	v_lshl_or_b32 v89, v125, 16, v106
	s_waitcnt lgkmcnt(1)
	v_pk_mul_f32 v[58:59], v[86:87], v[58:59]
	v_pk_mul_f32 v[56:57], v[84:85], v[56:57]
	v_lshl_or_b32 v84, v99, 16, v93
	v_lshl_or_b32 v85, v111, 16, v105
	v_lshl_or_b32 v86, v173, 16, v166
	v_lshl_or_b32 v87, v187, 16, v180
	v_lshl_or_b32 v90, v174, 16, v167
	v_lshl_or_b32 v91, v188, 16, v181
	v_mfma_f32_16x16x32_bf16 v[60:63], v[84:87], v[80:83], v[60:63]
	ds_read_b128 v[84:87], v149 offset:26432
	v_mfma_f32_16x16x32_bf16 v[64:67], v[88:91], v[80:83], v[64:67]
	s_waitcnt lgkmcnt(1)
	s_nop 4
	v_pk_mul_f32 v[62:63], v[74:75], v[62:63]
	v_pk_mul_f32 v[60:61], v[72:73], v[60:61]
	ds_read_b128 v[72:75], v149 offset:26496
	v_lshl_or_b32 v88, v102, 16, v96
	v_lshl_or_b32 v89, v163, 16, v108
	s_waitcnt lgkmcnt(1)
	v_pk_mul_f32 v[66:67], v[86:87], v[66:67]
	v_pk_mul_f32 v[64:65], v[84:85], v[64:65]
	v_lshl_or_b32 v84, v101, 16, v95
	v_lshl_or_b32 v85, v162, 16, v107
	v_lshl_or_b32 v86, v175, 16, v168
	v_lshl_or_b32 v87, v189, 16, v182
	v_lshl_or_b32 v90, v176, 16, v169
	v_lshl_or_b32 v91, v190, 16, v183
	v_mfma_f32_16x16x32_bf16 v[68:71], v[84:87], v[80:83], v[68:71]
	ds_read_b128 v[84:87], v149 offset:26560
	s_waitcnt lgkmcnt(1)
	s_nop 5
	v_pk_mul_f32 v[74:75], v[74:75], v[70:71]
	v_pk_mul_f32 v[72:73], v[72:73], v[68:69]
	v_mfma_f32_16x16x32_bf16 v[68:71], v[88:91], v[80:83], v[76:79]
	s_waitcnt lgkmcnt(0)
	s_nop 6
	v_pk_mul_f32 v[70:71], v[86:87], v[70:71]
	v_pk_mul_f32 v[68:69], v[84:85], v[68:69]
	s_cbranch_vccnz .LBB0_2411
	s_mov_b32 s76, s75
	s_branch .LBB0_2417
; DI void hgrn_scan_mfma(const Params& p, char* shm) {
;     ...
;         HG_LOAD(0, ra0, ra1, ra2, ra3, ra4); HG_LOAD(1, rb0, rb1, rb2, rb3, rb4);
;     ...
;             if (hh == 0) HG_STAGE(ch, ra0, ra1, ra2, ra3, ra4); else HG_STAGE(ch, rb0, rb1, rb2, rb3, rb4);
.Lscanh_2417:
	s_waitcnt vmcnt(7)
	v_lshlrev_b32_e32 v0, 16, v12
	v_and_b32_e32 v1, 0xffff0000, v12
	s_waitcnt vmcnt(6)
	v_lshlrev_b32_e32 v76, 16, v16
	v_and_b32_e32 v77, 0xffff0000, v16
	v_pk_mul_f32 v[0:1], v[0:1], v[76:77]
	v_lshlrev_b32_e32 v78, 16, v17
	v_cvt_pk_bf16_f32 v76, v0, v1
	v_lshlrev_b32_e32 v0, 16, v13
	v_and_b32_e32 v1, 0xffff0000, v13
	v_and_b32_e32 v79, 0xffff0000, v17
	v_pk_mul_f32 v[0:1], v[0:1], v[78:79]
	v_lshlrev_b32_e32 v78, 16, v18
	v_cvt_pk_bf16_f32 v77, v0, v1
	v_lshlrev_b32_e32 v0, 16, v14
	v_and_b32_e32 v1, 0xffff0000, v14
	v_and_b32_e32 v79, 0xffff0000, v18
	v_pk_mul_f32 v[0:1], v[0:1], v[78:79]
	v_lshlrev_b32_e32 v80, 16, v19
	v_cvt_pk_bf16_f32 v78, v0, v1
	v_lshlrev_b32_e32 v0, 16, v15
	v_and_b32_e32 v1, 0xffff0000, v15
	v_and_b32_e32 v81, 0xffff0000, v19
	v_pk_mul_f32 v[0:1], v[0:1], v[80:81]
	s_nop 0
	v_cvt_pk_bf16_f32 v79, v0, v1
	s_barrier
	ds_write_b128 v158, v[76:79]
	s_waitcnt vmcnt(5)
	ds_write_b128 v158, v[20:23] offset:8704
	s_waitcnt vmcnt(4)
	ds_write_b128 v158, v[24:27] offset:17408
	s_and_saveexec_b64 s[0:1], s[2:3]
	ds_write_b128 v159, v[4:7] offset:26112
	s_or_b64 exec, exec, s[0:1]
	s_add_i32 s75, s76, 2
	s_cmpk_lt_u32 s76, 0x46
	s_cselect_b64 s[56:57], -1, 0
	s_cmpk_gt_u32 s76, 0x45
	s_cselect_b64 s[54:55], -1, 0
	v_cndmask_b32_e64 v0, 0, 1, s[48:49]
	s_and_b64 vcc, exec, s[54:55]
	v_cmp_ne_u32_e64 s[0:1], 1, v0
	s_waitcnt lgkmcnt(0)
	s_barrier
	s_cbranch_vccnz .Lscanh_2429
	s_and_b64 vcc, exec, s[0:1]
	v_lshl_add_u32 v0, s75, 5, v113
	s_cbranch_vccnz .Lscanh_2426
	v_add3_u32 v1, v113, s74, 64
	v_cmp_lt_i32_e32 vcc, s47, v1
	s_and_saveexec_b64 s[14:15], vcc
	s_xor_b64 s[14:15], exec, s[14:15]
	v_add_u32_e32 v0, s38, v156
	v_add_u32_e32 v0, 0x9df, v0
	s_andn2_saveexec_b64 s[14:15], s[14:15]
	v_sub_u32_e32 v0, 0xff, v0
	s_or_b64 exec, exec, s[14:15]

; DI void hgrn_scan_mfma(const Params& p, char* shm) {
;     ...
;         HG_LOAD(0, ra0, ra1, ra2, ra3, ra4); HG_LOAD(1, rb0, rb1, rb2, rb3, rb4);
;         for (int ch2 = 0; ch2 < LT / C; ch2 += 2) {
; #pragma unroll
;           for (int hh = 0; hh < 2; ++hh) {
;             const int ch = ch2 + hh;
;             if (hh == 0) HG_STAGE(ch, ra0, ra1, ra2, ra3, ra4); else HG_STAGE(ch, rb0, rb1, rb2, rb3, rb4);
.Lscanh_2429:
	s_cmp_lt_u32 s76, 8
	s_cselect_b32 s77, 0xff, s58
	s_add_i32 s77, s77, s38
	s_add_i32 s78, s77, 32
	s_and_b64 s[14:15], s[12:13], exec
	s_waitcnt lgkmcnt(0)
	s_cselect_b32 s14, s74, s78
	s_add_u32 s14, s50, s14
	s_addc_u32 s15, s51, 0
	s_lshl_b64 s[14:15], s[14:15], 11
	s_waitcnt lgkmcnt(0)
	s_waitcnt lgkmcnt(0)
	s_waitcnt lgkmcnt(0)
	s_cmpk_gt_u32 s76, 0x45
	s_cbranch_scc0 .Lscanh_steady
	s_waitcnt vmcnt(0)
.Lscanh_steady:
	s_waitcnt vmcnt(7)
	v_lshlrev_b32_e32 v0, 16, v28
	v_and_b32_e32 v1, 0xffff0000, v28
	s_waitcnt lgkmcnt(0)
	s_barrier
	s_waitcnt vmcnt(6)
	v_lshlrev_b32_e32 v162, 16, v35
	v_and_b32_e32 v163, 0xffff0000, v35
	v_lshlrev_b32_e32 v68, 16, v32
	v_and_b32_e32 v69, 0xffff0000, v32
	v_pk_mul_f32 v[0:1], v[0:1], v[68:69]
	v_lshlrev_b32_e32 v70, 16, v33
	v_cvt_pk_bf16_f32 v68, v0, v1
	v_lshlrev_b32_e32 v0, 16, v29
	v_and_b32_e32 v1, 0xffff0000, v29
	v_and_b32_e32 v71, 0xffff0000, v33
	v_pk_mul_f32 v[0:1], v[0:1], v[70:71]
	v_lshlrev_b32_e32 v70, 16, v34
	v_cvt_pk_bf16_f32 v69, v0, v1
	v_lshlrev_b32_e32 v0, 16, v30
	v_and_b32_e32 v1, 0xffff0000, v30
	v_and_b32_e32 v71, 0xffff0000, v34
	v_pk_mul_f32 v[0:1], v[0:1], v[70:71]
	s_nop 0
	v_cvt_pk_bf16_f32 v70, v0, v1
	v_lshlrev_b32_e32 v0, 16, v31
	v_and_b32_e32 v1, 0xffff0000, v31
	v_pk_mul_f32 v[0:1], v[0:1], v[162:163]
	s_nop 0
	v_cvt_pk_bf16_f32 v71, v0, v1
	ds_write_b128 v158, v[68:71]
	s_waitcnt vmcnt(5)
	ds_write_b128 v158, v[36:39] offset:8704
	s_waitcnt vmcnt(4)
	ds_write_b128 v158, v[40:43] offset:17408
	s_and_saveexec_b64 s[14:15], s[2:3]
	ds_write_b128 v159, v[8:11] offset:26112
	s_or_b64 exec, exec, s[14:15]
	s_andn2_b64 vcc, exec, s[56:57]
	s_waitcnt lgkmcnt(0)
	s_barrier
	s_cbranch_vccnz .Lscanh_2441
	s_lshl_b32 s14, s76, 5
	s_addk_i32 s14, 0x60
	s_and_b64 vcc, exec, s[0:1]
	v_add_u32_e32 v0, s14, v113
	s_cbranch_vccnz .Lscanh_2438
	v_add_u32_e32 v1, s74, v113
	v_add_u32_e32 v1, 0x60, v1
	v_cmp_lt_i32_e32 vcc, s47, v1
	s_and_saveexec_b64 s[0:1], vcc
	s_xor_b64 s[0:1], exec, s[0:1]
	v_add_u32_e32 v0, s38, v156
	v_add_u32_e32 v0, 0x9bf, v0
	s_andn2_saveexec_b64 s[0:1], s[0:1]
	v_sub_u32_e32 v0, 0xff, v0
	s_or_b64 exec, exec, s[0:1]

; DI void hgrn_scan_mfma(const Params& p, char* shm) {
;     ...
;         for (int ch2 = 0; ch2 < LT / C; ch2 += 2) {
; #pragma unroll
;           for (int hh = 0; hh < 2; ++hh) {
;             const int ch = ch2 + hh;
;             if (hh == 0) HG_STAGE(ch, ra0, ra1, ra2, ra3, ra4); else HG_STAGE(ch, rb0, rb1, rb2, rb3, rb4);
.Lscanh_2441:
	s_add_i32 s14, s74, 32
	s_and_b64 s[0:1], s[12:13], exec
	s_cselect_b32 s0, s14, s77
	s_add_u32 s0, s50, s0
	s_addc_u32 s1, s51, 0
	s_lshl_b64 s[0:1], s[0:1], 11
	v_lshl_add_u64 v[144:145], v[144:145], 0, s[44:45]
	s_sub_i32 s38, s38, 64
	s_add_i32 s74, s74, 64
	s_and_b64 vcc, exec, s[54:55]
	s_waitcnt lgkmcnt(0)
	s_waitcnt lgkmcnt(0)
	s_cbranch_vccnz .LBB0_2411
	s_mov_b32 s76, s75
	s_branch .Lscanh_2417

; __global__ void __launch_bounds__(NTHR) fwd_megakernel(Params p) {
;     extern __shared__ __attribute__((aligned(16))) char shm[];
	.amdhsa_kernel _Z14fwd_megakernel6Params
		.amdhsa_group_segment_fixed_size 0
		.amdhsa_private_segment_fixed_size 0
		.amdhsa_kernarg_size 472
		.amdhsa_user_sgpr_count 2
		.amdhsa_user_sgpr_dispatch_ptr 0
		.amdhsa_user_sgpr_queue_ptr 0
		.amdhsa_user_sgpr_kernarg_segment_ptr 1
		.amdhsa_user_sgpr_dispatch_id 0
		.amdhsa_user_sgpr_kernarg_preload_length 0
		.amdhsa_user_sgpr_kernarg_preload_offset 0
		.amdhsa_user_sgpr_private_segment_size 0
		.amdhsa_uses_dynamic_stack 0
		.amdhsa_enable_private_segment 0
		.amdhsa_system_sgpr_workgroup_id_x 1
		.amdhsa_system_sgpr_workgroup_id_y 0
		.amdhsa_system_sgpr_workgroup_id_z 0
		.amdhsa_system_sgpr_workgroup_info 0
		.amdhsa_system_vgpr_workitem_id 2
		.amdhsa_next_free_vgpr 255
		.amdhsa_next_free_sgpr 102
		.amdhsa_accum_offset 256
		.amdhsa_reserve_vcc 1
		.amdhsa_float_round_mode_32 0
		.amdhsa_float_round_mode_16_64 0
		.amdhsa_float_denorm_mode_32 3
		.amdhsa_float_denorm_mode_16_64 3
		.amdhsa_dx10_clamp 1
		.amdhsa_ieee_mode 1
		.amdhsa_fp16_overflow 0
		.amdhsa_tg_split 0
		.amdhsa_exception_fp_ieee_invalid_op 0
		.amdhsa_exception_fp_denorm_src 0
		.amdhsa_exception_fp_ieee_div_zero 0
		.amdhsa_exception_fp_ieee_overflow 0
		.amdhsa_exception_fp_ieee_underflow 0
		.amdhsa_exception_fp_ieee_inexact 0
		.amdhsa_exception_int_div_zero 0
	.end_amdhsa_kernel

; __global__ void __launch_bounds__(NTHR) fwd_megakernel(Params p) {
;     extern __shared__ __attribute__((aligned(16))) char shm[];
amdhsa.kernels:
  - .agpr_count:     0
    .args:
      - .offset:         0
        .size:           216
        .value_kind:     by_value
      - .offset:         216
        .size:           4
        .value_kind:     hidden_block_count_x
      - .offset:         220
        .size:           4
        .value_kind:     hidden_block_count_y
      - .offset:         224
        .size:           4
        .value_kind:     hidden_block_count_z
      - .offset:         228
        .size:           2
        .value_kind:     hidden_group_size_x
      - .offset:         230
        .size:           2
        .value_kind:     hidden_group_size_y
      - .offset:         232
        .size:           2
        .value_kind:     hidden_group_size_z
      - .offset:         234
        .size:           2
        .value_kind:     hidden_remainder_x
      - .offset:         236
        .size:           2
        .value_kind:     hidden_remainder_y
      - .offset:         238
        .size:           2
        .value_kind:     hidden_remainder_z
      - .offset:         256
        .size:           8
        .value_kind:     hidden_global_offset_x
      - .offset:         264
        .size:           8
        .value_kind:     hidden_global_offset_y
      - .offset:         272
        .size:           8
        .value_kind:     hidden_global_offset_z
      - .offset:         280
        .size:           2
        .value_kind:     hidden_grid_dims
      - .offset:         304
        .size:           8
        .value_kind:     hidden_multigrid_sync_arg
      - .offset:         336
        .size:           4
        .value_kind:     hidden_dynamic_lds_size
    .group_segment_fixed_size: 0
    .kernarg_segment_align: 8
    .kernarg_segment_size: 472
    .language:       OpenCL C
    .language_version:
      - 2
      - 0
    .max_flat_workgroup_size: 512
    .name:           _Z14fwd_megakernel6Params
    .private_segment_fixed_size: 0
    .sgpr_count:     108
    .sgpr_spill_count: 65
    .symbol:         _Z14fwd_megakernel6Params.kd
    .uniform_work_group_size: 1
    .uses_dynamic_stack: false
    .vgpr_count:     255
    .vgpr_spill_count: 0
    .wavefront_size: 64
